# v007 plus GEMM phase prologue de-serialised: all 14 stage loads in flight before the first wait, first barrier moved after vmcnt(6)
# baseline (speedup 1.0000x reference)
; #define PG8_STAGE(bufoff, gbase, voff) do { _Pragma("unroll") for (int _i = 0; _i < 2; ++_i) \
;     __builtin_amdgcn_global_load_lds((const unsigned*)((const char*)(gbase) + (voff)[_i]), (LAS unsigned*)(lds + (bufoff) + ldsw + _i * 8192), 16, 0, 0); } while (0)
; #define PG8_WAIT_V(n) asm volatile("s_waitcnt vmcnt(" #n ")" ::: "memory")
; #define PG8_BAR __builtin_amdgcn_s_barrier()
; template <class Epi, bool HOOK>
; __device__ __forceinline__ void gemm_phase(LAS unsigned char* lds, const Gemm g, const StaticOrder& S, const Epi& E, const int hook_t) {
;     ...
;   for (int i = 0; i < 2; ++i) { int R, C; stage_rc(tid * 16 + i * 8192, R, C);
;     voffA[i] = (unsigned)(R * g.lda + C) * 2u; voffB[i] = (unsigned)(R * g.ldb + C) * 2u; }
;   const size_t kstep = (size_t)(BK * 2);
;   const size_t hstepA = (size_t)HALF * g.lda * 2, hstepB = (size_t)HALF * g.ldb * 2;
;   const size_t tstepA = 2 * hstepA, tstepB = 2 * hstepB;
;   const unsigned ldsw = (unsigned)wid * 1024u;
;   const int aoff = lds_byte(wr * 64 + fr, fq * 8), boff = lds_byte(wc * 32 + fr, fq * 8);
;     ...
;   PG8_STAGE(PG8_SB(0, 0), cB, voffB); PG8_STAGE(PG8_SA(0, 0), cA, voffA); PG8_STAGE(PG8_SB(0, 1), cB + hstepB, voffB); PG8_STAGE(PG8_SA(0, 1), cA + hstepA, voffA);
;   if (wr == 1) PG8_BAR;
;   PG8_WAIT_V(4); PG8_BAR;
;   PG8_STAGE(PG8_SB(1, 0), cB + kstep, voffB); PG8_STAGE(PG8_SA(1, 0), cA + kstep, voffA); PG8_STAGE(PG8_SB(1, 1), cB + hstepB + kstep, voffB);
;   PG8_WAIT_V(6); PG8_BAR;
.LBB0_46:
	v_lshrrev_b32_e32 v20, 1, v18
	v_and_b32_e32 v20, 24, v20
	v_and_b32_e32 v19, 15, v18
	v_lshlrev_b32_e32 v21, 1, v20
	v_lshlrev_b32_e32 v18, 2, v18
	s_sext_i32_i8 s18, s0
	v_lshl_or_b32 v156, s1, 6, v19
	v_lshl_or_b32 v19, v19, 6, v21
	s_lshl_b32 s0, s1, 13
	v_and_b32_e32 v18, 32, v18
	v_bitop3_b32 v21, v19, s0, v18 bitop3:0xde
	s_lshl_b32 s0, s4, 5
	s_and_b32 s4, s0, 0x60
	s_add_i32 m0, s28, 0x18000
	v_lshl_add_u64 v[8:9], v[8:9], 0, s[56:57]
	s_lshl_b32 s0, s4, 7
	global_load_lds_dwordx4 v[8:9], off
	v_lshl_add_u64 v[6:7], v[6:7], 0, s[56:57]
	s_add_i32 m0, s28, 0x1a000
	s_add_i32 s34, s28, 0x8000
	s_add_i32 s35, s28, 0xa000
	v_bitop3_b32 v157, v19, s0, v18 bitop3:0xde
	global_load_lds_dwordx4 v[6:7], off
	v_lshl_add_u64 v[4:5], v[4:5], 0, s[56:57]
	s_mov_b32 m0, s34
	s_add_u32 s0, s16, 0x50080
	global_load_lds_dwordx4 v[4:5], off
	v_lshl_add_u64 v[2:3], v[2:3], 0, s[56:57]
	s_mov_b32 m0, s35
	s_addc_u32 s1, s17, 0
	global_load_lds_dwordx4 v[2:3], off
	s_add_i32 m0, s28, 0x1c000
	v_lshl_add_u64 v[2:3], s[0:1], 0, v[0:1]
	global_load_lds_dwordx4 v[2:3], off
	v_lshl_add_u64 v[2:3], s[0:1], 0, v[130:131]
	s_add_i32 m0, s28, 0x1e000
	v_readlane_b32 s0, v252, 31
	global_load_lds_dwordx4 v[2:3], off
	v_or_b32_e32 v158, s4, v20
	s_movk_i32 s4, 0x500
	v_readlane_b32 s1, v252, 32
	v_lshrrev_b32_e32 v3, 1, v10
	v_mul_lo_u32 v2, v12, s4
	s_movk_i32 s5, 0x5000
	s_and_b64 s[0:1], s[0:1], exec
	v_mad_u64_u32 v[2:3], s[0:1], v3, s5, v[2:3]
	v_or_b32_e32 v2, v2, v11
	v_add_lshl_u32 v132, v2, v13, 1
	v_lshrrev_b32_e32 v3, 1, v14
	v_mul_lo_u32 v2, v16, s4
	s_waitcnt vmcnt(6)
	s_barrier
	v_mad_u64_u32 v[2:3], s[0:1], v3, s5, v[2:3]
	v_or_b32_e32 v2, v2, v15
	s_cselect_b32 s36, 5, 6
	v_mov_b32_e32 v133, v1
	v_add_lshl_u32 v134, v2, v17, 1
	v_mov_b32_e32 v135, v1
	s_mov_b32 s37, 0
	v_add_u32_e32 v159, 0, v21
	s_barrier
	s_branch .LBB0_48

; #define PG8_STAGE(bufoff, gbase, voff) do { _Pragma("unroll") for (int _i = 0; _i < 2; ++_i) \
;     __builtin_amdgcn_global_load_lds((const unsigned*)((const char*)(gbase) + (voff)[_i]), (LAS unsigned*)(lds + (bufoff) + ldsw + _i * 8192), 16, 0, 0); } while (0)
; #define PG8_WAIT_V(n) asm volatile("s_waitcnt vmcnt(" #n ")" ::: "memory")
; #define PG8_BAR __builtin_amdgcn_s_barrier()
; template <class Epi, bool HOOK>
; __device__ __forceinline__ void gemm_phase(LAS unsigned char* lds, const Gemm g, const StaticOrder& S, const Epi& E, const int hook_t) {
;     ...
;   for (int i = 0; i < 2; ++i) { int R, C; stage_rc(tid * 16 + i * 8192, R, C);
;     voffA[i] = (unsigned)(R * g.lda + C) * 2u; voffB[i] = (unsigned)(R * g.ldb + C) * 2u; }
;   const size_t kstep = (size_t)(BK * 2);
;   const size_t hstepA = (size_t)HALF * g.lda * 2, hstepB = (size_t)HALF * g.ldb * 2;
;   const size_t tstepA = 2 * hstepA, tstepB = 2 * hstepB;
;   const unsigned ldsw = (unsigned)wid * 1024u;
;   const int aoff = lds_byte(wr * 64 + fr, fq * 8), boff = lds_byte(wc * 32 + fr, fq * 8);
;     ...
;   PG8_STAGE(PG8_SB(0, 0), cB, voffB); PG8_STAGE(PG8_SA(0, 0), cA, voffA); PG8_STAGE(PG8_SB(0, 1), cB + hstepB, voffB); PG8_STAGE(PG8_SA(0, 1), cA + hstepA, voffA);
;   if (wr == 1) PG8_BAR;
;   PG8_WAIT_V(4); PG8_BAR;
;   PG8_STAGE(PG8_SB(1, 0), cB + kstep, voffB); PG8_STAGE(PG8_SA(1, 0), cA + kstep, voffA); PG8_STAGE(PG8_SB(1, 1), cB + hstepB + kstep, voffB);
;   PG8_WAIT_V(6); PG8_BAR;
.LBB0_118:
	s_add_u32 s14, s54, s0
	s_addc_u32 s15, s55, s1
	s_add_i32 m0, s31, 0x18000
	v_lshl_add_u64 v[2:3], v[2:3], 0, s[56:57]
	global_load_lds_dwordx4 v[2:3], off
	v_lshl_add_u64 v[2:3], v[4:5], 0, s[56:57]
	s_add_i32 m0, s31, 0x1a000
	s_add_i32 s38, s31, 0x8000
	global_load_lds_dwordx4 v[2:3], off
	v_lshl_add_u64 v[2:3], v[6:7], 0, s[56:57]
	s_mov_b32 m0, s38
	s_add_i32 s39, s31, 0xa000
	global_load_lds_dwordx4 v[2:3], off
	v_lshl_add_u64 v[2:3], v[8:9], 0, s[56:57]
	s_mov_b32 m0, s39
	v_lshrrev_b32_e32 v22, 1, v20
	global_load_lds_dwordx4 v[2:3], off
	s_add_i32 m0, s31, 0x1c000
	v_lshl_add_u64 v[2:3], v[10:11], 0, s[56:57]
	global_load_lds_dwordx4 v[2:3], off
	v_lshl_add_u64 v[2:3], v[12:13], 0, s[56:57]
	s_add_i32 m0, s31, 0x1e000
	v_and_b32_e32 v22, 24, v22
	global_load_lds_dwordx4 v[2:3], off
	v_and_b32_e32 v21, 15, v20
	v_lshlrev_b32_e32 v23, 1, v22
	v_lshlrev_b32_e32 v20, 2, v20
	v_lshl_or_b32 v136, s6, 6, v21
	v_lshl_or_b32 v21, v21, 6, v23
	s_lshl_b32 s0, s6, 13
	v_and_b32_e32 v20, 32, v20
	v_add_u32_e32 v2, v17, v18
	v_bitop3_b32 v23, v21, s0, v20 bitop3:0xde
	s_lshl_b32 s0, s5, 5
	v_add_lshl_u32 v2, v2, v19, 1
	v_mov_b32_e32 v3, v1
	s_and_b32 s0, s0, 0x60
	s_waitcnt vmcnt(6)
	s_barrier
	v_lshl_add_u64 v[132:133], s[50:51], 0, v[2:3]
	v_add_u32_e32 v2, v14, v15
	s_lshr_b32 s37, s20, 6
	s_lshl_b32 s1, s0, 7
	v_add_lshl_u32 v2, v2, v16, 1
	s_sext_i32_i16 s43, s4
	v_bitop3_b32 v137, v21, s1, v20 bitop3:0xde
	s_add_i32 s41, s37, -2
	s_mov_b32 s11, s51
	v_or_b32_e32 v138, s0, v22
	v_lshl_add_u64 v[134:135], s[50:51], 0, v[2:3]
	s_mov_b32 s42, 0
	v_add_u32_e32 v139, 0, v23
	s_barrier

; #define PG8_STAGE(bufoff, gbase, voff) do { _Pragma("unroll") for (int _i = 0; _i < 2; ++_i) \
;     __builtin_amdgcn_global_load_lds((const unsigned*)((const char*)(gbase) + (voff)[_i]), (LAS unsigned*)(lds + (bufoff) + ldsw + _i * 8192), 16, 0, 0); } while (0)
; #define PG8_WAIT_V(n) asm volatile("s_waitcnt vmcnt(" #n ")" ::: "memory")
; #define PG8_BAR __builtin_amdgcn_s_barrier()
; template <class Epi, bool HOOK>
; __device__ __forceinline__ void gemm_phase(LAS unsigned char* lds, const Gemm g, const StaticOrder& S, const Epi& E, const int hook_t) {
;     ...
;   for (int i = 0; i < 2; ++i) { int R, C; stage_rc(tid * 16 + i * 8192, R, C);
;     voffA[i] = (unsigned)(R * g.lda + C) * 2u; voffB[i] = (unsigned)(R * g.ldb + C) * 2u; }
;   const size_t kstep = (size_t)(BK * 2);
;   const size_t hstepA = (size_t)HALF * g.lda * 2, hstepB = (size_t)HALF * g.ldb * 2;
;   const size_t tstepA = 2 * hstepA, tstepB = 2 * hstepB;
;   const unsigned ldsw = (unsigned)wid * 1024u;
;   const int aoff = lds_byte(wr * 64 + fr, fq * 8), boff = lds_byte(wc * 32 + fr, fq * 8);
;     ...
;   PG8_STAGE(PG8_SB(0, 0), cB, voffB); PG8_STAGE(PG8_SA(0, 0), cA, voffA); PG8_STAGE(PG8_SB(0, 1), cB + hstepB, voffB); PG8_STAGE(PG8_SA(0, 1), cA + hstepA, voffA);
;   if (wr == 1) PG8_BAR;
;   PG8_WAIT_V(4); PG8_BAR;
;   PG8_STAGE(PG8_SB(1, 0), cB + kstep, voffB); PG8_STAGE(PG8_SA(1, 0), cA + kstep, voffA); PG8_STAGE(PG8_SB(1, 1), cB + hstepB + kstep, voffB);
;   PG8_WAIT_V(6); PG8_BAR;
.LBB0_140:
	s_sext_i32_i8 s17, s4
	v_and_b32_e32 v16, 48, v15
	v_lshlrev_b32_e32 v17, 6, v15
	s_movk_i32 s4, 0x3c0
	v_lshlrev_b32_e32 v15, 2, v15
	s_lshl_b32 s93, s1, 6
	s_lshl_b32 s1, s1, 13
	v_and_or_b32 v16, v17, s4, v16
	v_and_b32_e32 v15, 32, v15
	v_bitop3_b32 v17, v16, s1, v15 bitop3:0xde
	s_lshl_b32 s1, s3, 5
	s_and_b32 s50, s1, 0x60
	s_add_i32 m0, s67, 0x18000
	v_lshl_add_u64 v[8:9], v[8:9], 0, s[56:57]
	s_lshl_b32 s1, s50, 7
	global_load_lds_dwordx4 v[8:9], off
	v_lshl_add_u64 v[6:7], v[6:7], 0, s[56:57]
	s_add_i32 m0, s67, 0x1a000
	s_add_i32 s91, s67, 0x8000
	s_add_i32 s3, s67, 0xa000
	global_load_lds_dwordx4 v[6:7], off
	v_lshl_add_u64 v[4:5], v[4:5], 0, s[56:57]
	s_mov_b32 m0, s91
	s_add_u32 s4, s70, 0x40080
	global_load_lds_dwordx4 v[4:5], off
	v_lshl_add_u64 v[2:3], v[2:3], 0, s[56:57]
	s_mov_b32 m0, s3
	s_addc_u32 s5, s71, 0
	global_load_lds_dwordx4 v[2:3], off
	s_add_i32 m0, s67, 0x1c000
	v_lshl_add_u64 v[2:3], s[4:5], 0, v[154:155]
	global_load_lds_dwordx4 v[2:3], off
	v_lshl_add_u64 v[2:3], s[4:5], 0, v[156:157]
	s_add_i32 m0, s67, 0x1e000
	v_readlane_b32 s4, v252, 31
	global_load_lds_dwordx4 v[2:3], off
	v_lshlrev_b32_e32 v2, 14, v0
	v_and_b32_e32 v2, 0xffff8000, v2
	v_lshl_add_u32 v2, v10, 11, v2
	v_and_b32_e32 v0, 1, v0
	v_lshl_or_b32 v0, v0, 6, v2
	v_lshl_add_u32 v158, v11, 1, v0
	v_lshlrev_b32_e32 v0, 14, v12
	v_and_b32_e32 v0, 0xffff8000, v0
	s_waitcnt vmcnt(6)
	s_barrier
	v_readlane_b32 s5, v252, 32
	v_lshl_add_u32 v0, v13, 11, v0
	v_and_b32_e32 v2, 1, v12
	s_and_b64 s[4:5], s[4:5], exec
	v_lshl_or_b32 v0, v2, 6, v0
	v_bitop3_b32 v164, s1, v16, v15 bitop3:0xf6
	s_mov_b32 s1, s51
	s_cselect_b32 s4, 5, 6
	v_mov_b32_e32 v159, v1
	v_lshl_add_u32 v160, v14, 1, v0
	v_mov_b32_e32 v161, v1
	s_mov_b32 s52, 0
	v_add_u32_e32 v165, 0, v17
	s_barrier
	v_writelane_b32 v252, s4, 42
	s_branch .LBB0_142

; #define PG8_STAGE(bufoff, gbase, voff) do { _Pragma("unroll") for (int _i = 0; _i < 2; ++_i) \
;     __builtin_amdgcn_global_load_lds((const unsigned*)((const char*)(gbase) + (voff)[_i]), (LAS unsigned*)(lds + (bufoff) + ldsw + _i * 8192), 16, 0, 0); } while (0)
; #define PG8_WAIT_V(n) asm volatile("s_waitcnt vmcnt(" #n ")" ::: "memory")
; #define PG8_BAR __builtin_amdgcn_s_barrier()
; template <class Epi, bool HOOK>
; __device__ __forceinline__ void gemm_phase(LAS unsigned char* lds, const Gemm g, const StaticOrder& S, const Epi& E, const int hook_t) {
;     ...
;   for (int i = 0; i < 2; ++i) { int R, C; stage_rc(tid * 16 + i * 8192, R, C);
;     voffA[i] = (unsigned)(R * g.lda + C) * 2u; voffB[i] = (unsigned)(R * g.ldb + C) * 2u; }
;   const size_t kstep = (size_t)(BK * 2);
;   const size_t hstepA = (size_t)HALF * g.lda * 2, hstepB = (size_t)HALF * g.ldb * 2;
;   const size_t tstepA = 2 * hstepA, tstepB = 2 * hstepB;
;   const unsigned ldsw = (unsigned)wid * 1024u;
;   const int aoff = lds_byte(wr * 64 + fr, fq * 8), boff = lds_byte(wc * 32 + fr, fq * 8);
;     ...
;   PG8_STAGE(PG8_SB(0, 0), cB, voffB); PG8_STAGE(PG8_SA(0, 0), cA, voffA); PG8_STAGE(PG8_SB(0, 1), cB + hstepB, voffB); PG8_STAGE(PG8_SA(0, 1), cA + hstepA, voffA);
;   if (wr == 1) PG8_BAR;
;   PG8_WAIT_V(4); PG8_BAR;
;   PG8_STAGE(PG8_SB(1, 0), cB + kstep, voffB); PG8_STAGE(PG8_SA(1, 0), cA + kstep, voffA); PG8_STAGE(PG8_SB(1, 1), cB + hstepB + kstep, voffB);
;   PG8_WAIT_V(6); PG8_BAR;
.LBB0_211:
	v_readlane_b32 s1, v252, 33
	s_add_i32 s30, s1, -1
	s_and_b32 s1, s3, 3
	s_add_i32 m0, s19, 0x18000
	v_lshl_add_u64 v[8:9], v[8:9], 0, s[56:57]
	s_lshl_b32 s3, s4, 13
	s_lshl_b32 s5, s1, 12
	global_load_lds_dwordx4 v[8:9], off
	v_lshl_add_u64 v[6:7], v[6:7], 0, s[56:57]
	s_add_i32 m0, s19, 0x1a000
	s_add_i32 s31, s19, 0x8000
	s_add_i32 s34, s19, 0xa000
	global_load_lds_dwordx4 v[6:7], off
	v_lshl_add_u64 v[4:5], v[4:5], 0, s[56:57]
	s_mov_b32 m0, s31
	s_add_u32 s10, s20, 0x40080
	global_load_lds_dwordx4 v[4:5], off
	v_lshl_add_u64 v[2:3], v[2:3], 0, s[56:57]
	s_mov_b32 m0, s34
	s_addc_u32 s11, s21, 0
	global_load_lds_dwordx4 v[2:3], off
	s_add_i32 m0, s19, 0x1c000
	v_lshl_add_u64 v[2:3], s[10:11], 0, v[138:139]
	global_load_lds_dwordx4 v[2:3], off
	v_lshl_add_u64 v[2:3], s[10:11], 0, v[140:141]
	s_add_i32 m0, s19, 0x1e000
	s_lshr_b32 s35, s8, 3
	global_load_lds_dwordx4 v[2:3], off
	v_lshrrev_b32_e32 v2, 1, v0
	v_and_b32_e32 v2, 24, v2
	v_and_b32_e32 v3, 15, v0
	v_lshlrev_b32_e32 v4, 1, v2
	v_lshlrev_b32_e32 v0, 2, v0
	v_lshl_or_b32 v190, s4, 6, v3
	v_lshl_or_b32 v3, v3, 6, v4
	v_and_b32_e32 v0, 32, v0
	v_bitop3_b32 v191, v3, s5, v0 bitop3:0xde
	v_readlane_b32 s4, v253, 55
	v_bitop3_b32 v4, v3, s3, v0 bitop3:0xde
	v_lshlrev_b32_e32 v0, 2, v2
	v_readlane_b32 s5, v253, 56
	v_and_b32_e32 v3, 1, v10
	s_waitcnt vmcnt(6)
	s_barrier
	v_lshl_or_b32 v192, s1, 5, v2
	v_lshl_add_u64 v[142:143], s[4:5], 0, v[0:1]
	v_readlane_b32 s4, v253, 57
	v_readlane_b32 s5, v253, 58
	s_lshl_b32 s1, s1, 6
	v_readlane_b32 s3, v253, 59
	v_lshl_add_u64 v[144:145], s[4:5], 0, v[0:1]
	v_lshlrev_b32_e32 v0, 14, v10
	v_and_b32_e32 v0, 0xffff8000, v0
	v_lshl_add_u32 v0, v11, 11, v0
	v_lshl_or_b32 v0, v3, 6, v0
	s_lshl_b32 s4, s78, 10
	v_lshl_add_u32 v146, v12, 1, v0
	v_lshlrev_b32_e32 v0, 14, v13
	s_ashr_i32 s5, s4, 31
	v_and_b32_e32 v0, 0xffff8000, v0
	s_lshl_b64 s[4:5], s[4:5], 2
	v_lshl_add_u32 v0, v14, 11, v0
	v_and_b32_e32 v3, 1, v13
	s_add_u32 s36, s3, s4
	v_readlane_b32 s3, v253, 60
	v_lshl_or_b32 v0, v3, 6, v0
	v_readlane_b32 s52, v252, 25
	s_mov_b32 s9, s51
	s_addc_u32 s37, s3, s5
	v_mov_b32_e32 v147, v1
	v_lshl_add_u32 v148, v15, 1, v0
	v_mov_b32_e32 v149, v1
	s_mov_b32 s38, 0
	v_add_u32_e32 v193, 0, v4
	s_lshl_b32 s39, s1, 1
	v_lshlrev_b32_e32 v150, 1, v2
	v_readlane_b32 s53, v252, 26
	s_barrier
	s_branch .LBB0_213
